# P4 EpiBr epilogue: GA/GL gate loads batched per 128-row half (kind 0) or per tile (kind 1) instead of per 8-column group
# speedup vs baseline: 1.0176x; 1.0176x over previous
;     __device__ __forceinline__ void operator()(f32x4 (&acc)[2][2][4][2], const pg8::Unit& u, int wr, int wc, int fr, int fq) const {
;         const int row0 = u.pm * 256 + wr * 64 + fr, colt = u.pn * 256 + wc * 32 + 8 * fq;
; #pragma unroll
;         for (int ai = 0; ai < 2; ++ai)
; #pragma unroll
;             for (int m = 0; m < 4; ++m) { const size_t ro = (size_t)(row0 + ai * 128 + m * 16) * DM + colt;
; #pragma unroll
;                 for (int bj = 0; bj < 2; ++bj) { const size_t o = ro + bj * 128;
;                     const u32x4 ga = *(const u32x4*)(GA + o);
;                     float a8[8] = {bflo(ga.x), bfhi(ga.x), bflo(ga.y), bfhi(ga.y), bflo(ga.z), bfhi(ga.z), bflo(ga.w), bfhi(ga.w)};
; #pragma unroll
;                     for (int e = 0; e < 8; ++e) a8[e] = fmaxf(a8[e], 1e-30f);
;                     if (u.kind == 0) { const u32x4 gl = *(const u32x4*)(GL + o);
;                         const float l8[8] = {bflo(gl.x), bfhi(gl.x), bflo(gl.y), bfhi(gl.y), bflo(gl.z), bfhi(gl.z), bflo(gl.w), bfhi(gl.w)};
; #pragma unroll
;                         for (int e = 0; e < 4; ++e) { acc[ai][bj][m][0][e] *= l8[e] * __builtin_amdgcn_rcpf(a8[e]); acc[ai][bj][m][1][e] *= l8[4 + e] * __builtin_amdgcn_rcpf(a8[4 + e]); }
.LBB0_651:
	v_readlane_b32 s58, v247, 26
	v_readlane_b32 s59, v247, 27
	v_readlane_b32 s60, v247, 29
	v_readlane_b32 s61, v247, 30
	s_lshl_b32 s21, s56, 8
	s_or_b32 s21, s21, s47
	v_ashrrev_i32_e32 v156, 1, v158
	v_and_b32_e32 v156, -8, v156
	v_add_u32_e32 v156, s21, v156
	v_and_or_b32 v157, v158, 15, s46
	v_lshl_add_u32 v157, s4, 8, v157
	v_lshlrev_b32_e32 v234, 11, v157
	v_lshl_add_u32 v234, v156, 1, v234
	s_mov_b64 s[98:99], s[78:79]
	s_cmp_lg_u32 s5, 0
	s_cselect_b64 s[28:29], -1, 0
	s_cbranch_scc1 .Lbr_kind1
	s_mov_b64 s[100:101], s[66:67]
	global_load_dwordx4 v[140:143], v234, s[98:99]
	global_load_dwordx4 v[178:181], v234, s[100:101]
	global_load_dwordx4 v[144:147], v234, s[98:99] offset:256
	global_load_dwordx4 v[186:189], v234, s[100:101] offset:256
	s_add_u32 s98, s98, 0x8000
	s_addc_u32 s99, s99, 0
	s_add_u32 s100, s100, 0x8000
	s_addc_u32 s101, s101, 0
	global_load_dwordx4 v[148:151], v234, s[98:99]
	global_load_dwordx4 v[190:193], v234, s[100:101]
	global_load_dwordx4 v[152:155], v234, s[98:99] offset:256
	global_load_dwordx4 v[194:197], v234, s[100:101] offset:256
	s_add_u32 s98, s98, 0x8000
	s_addc_u32 s99, s99, 0
	s_add_u32 s100, s100, 0x8000
	s_addc_u32 s101, s101, 0
	global_load_dwordx4 v[162:165], v234, s[98:99]
	global_load_dwordx4 v[198:201], v234, s[100:101]
	global_load_dwordx4 v[166:169], v234, s[98:99] offset:256
	global_load_dwordx4 v[202:205], v234, s[100:101] offset:256
	s_add_u32 s98, s98, 0x8000
	s_addc_u32 s99, s99, 0
	s_add_u32 s100, s100, 0x8000
	s_addc_u32 s101, s101, 0
	global_load_dwordx4 v[170:173], v234, s[98:99]
	global_load_dwordx4 v[206:209], v234, s[100:101]
	global_load_dwordx4 v[174:177], v234, s[98:99] offset:256
	global_load_dwordx4 v[210:213], v234, s[100:101] offset:256
	s_add_u32 s98, s98, 0x28000
	s_addc_u32 s99, s99, 0
	s_add_u32 s100, s100, 0x28000
	s_addc_u32 s101, s101, 0
	s_waitcnt vmcnt(0)
	v_lshlrev_b32_e32 v214, 16, v140
	v_and_b32_e32 v215, 0xffff0000, v140
	v_lshlrev_b32_e32 v216, 16, v141
	v_and_b32_e32 v217, 0xffff0000, v141
	v_lshlrev_b32_e32 v218, 16, v142
	v_and_b32_e32 v219, 0xffff0000, v142
	v_lshlrev_b32_e32 v220, 16, v143
	v_and_b32_e32 v221, 0xffff0000, v143
	v_max_f32_e32 v214, v214, v214
	v_max_f32_e32 v215, v215, v215
	v_max_f32_e32 v216, v216, v216
	v_max_f32_e32 v217, v217, v217
	v_max_f32_e32 v218, v218, v218
	v_max_f32_e32 v219, v219, v219
	v_max_f32_e32 v220, v220, v220
	v_max_f32_e32 v221, v221, v221
	v_max_f32_e32 v214, 0xda24260, v214
	v_max_f32_e32 v215, 0xda24260, v215
	v_max_f32_e32 v216, 0xda24260, v216
	v_max_f32_e32 v217, 0xda24260, v217
	v_max_f32_e32 v218, 0xda24260, v218
	v_max_f32_e32 v219, 0xda24260, v219
	v_max_f32_e32 v220, 0xda24260, v220
	v_max_f32_e32 v221, 0xda24260, v221
	v_rcp_f32_e32 v214, v214
	v_rcp_f32_e32 v215, v215
	v_rcp_f32_e32 v216, v216
	v_rcp_f32_e32 v217, v217
	v_rcp_f32_e32 v218, v218
	v_rcp_f32_e32 v219, v219
	v_rcp_f32_e32 v220, v220
	v_rcp_f32_e32 v221, v221
	v_lshlrev_b32_e32 v222, 16, v178
	v_and_b32_e32 v223, 0xffff0000, v178
	v_lshlrev_b32_e32 v224, 16, v179
	v_and_b32_e32 v225, 0xffff0000, v179
	v_lshlrev_b32_e32 v226, 16, v180
	v_and_b32_e32 v227, 0xffff0000, v180
	v_lshlrev_b32_e32 v228, 16, v181
	v_and_b32_e32 v229, 0xffff0000, v181
	v_pk_mul_f32 v[214:215], v[214:215], v[222:223]
	v_pk_mul_f32 v[216:217], v[216:217], v[224:225]
	v_pk_mul_f32 v[218:219], v[218:219], v[226:227]
	v_pk_mul_f32 v[220:221], v[220:221], v[228:229]
	v_pk_mul_f32 v[124:125], v[124:125], v[214:215]
	v_pk_mul_f32 v[126:127], v[126:127], v[216:217]
	v_pk_mul_f32 v[120:121], v[120:121], v[218:219]
	v_pk_mul_f32 v[122:123], v[122:123], v[220:221]
	v_lshlrev_b32_e32 v214, 16, v144
	v_and_b32_e32 v215, 0xffff0000, v144
	v_lshlrev_b32_e32 v216, 16, v145
	v_and_b32_e32 v217, 0xffff0000, v145
	v_lshlrev_b32_e32 v218, 16, v146
	v_and_b32_e32 v219, 0xffff0000, v146
	v_lshlrev_b32_e32 v220, 16, v147
	v_and_b32_e32 v221, 0xffff0000, v147
	v_max_f32_e32 v214, v214, v214
	v_max_f32_e32 v215, v215, v215
	v_max_f32_e32 v216, v216, v216
	v_max_f32_e32 v217, v217, v217
	v_max_f32_e32 v218, v218, v218
	v_max_f32_e32 v219, v219, v219
	v_max_f32_e32 v220, v220, v220
	v_max_f32_e32 v221, v221, v221
	v_max_f32_e32 v214, 0xda24260, v214
	v_max_f32_e32 v215, 0xda24260, v215
	v_max_f32_e32 v216, 0xda24260, v216
	v_max_f32_e32 v217, 0xda24260, v217
	v_max_f32_e32 v218, 0xda24260, v218
	v_max_f32_e32 v219, 0xda24260, v219
	v_max_f32_e32 v220, 0xda24260, v220
	v_max_f32_e32 v221, 0xda24260, v221
	v_rcp_f32_e32 v214, v214
	v_rcp_f32_e32 v215, v215
	v_rcp_f32_e32 v216, v216
	v_rcp_f32_e32 v217, v217
	v_rcp_f32_e32 v218, v218
	v_rcp_f32_e32 v219, v219
	v_rcp_f32_e32 v220, v220
	v_rcp_f32_e32 v221, v221
	v_lshlrev_b32_e32 v222, 16, v186
	v_and_b32_e32 v223, 0xffff0000, v186
	v_lshlrev_b32_e32 v224, 16, v187
	v_and_b32_e32 v225, 0xffff0000, v187
	v_lshlrev_b32_e32 v226, 16, v188
	v_and_b32_e32 v227, 0xffff0000, v188
	v_lshlrev_b32_e32 v228, 16, v189
	v_and_b32_e32 v229, 0xffff0000, v189
	v_pk_mul_f32 v[214:215], v[214:215], v[222:223]
	v_pk_mul_f32 v[216:217], v[216:217], v[224:225]
	v_pk_mul_f32 v[218:219], v[218:219], v[226:227]
	v_pk_mul_f32 v[220:221], v[220:221], v[228:229]
	v_pk_mul_f32 v[92:93], v[92:93], v[214:215]
	v_pk_mul_f32 v[94:95], v[94:95], v[216:217]
	v_pk_mul_f32 v[88:89], v[88:89], v[218:219]
	v_pk_mul_f32 v[90:91], v[90:91], v[220:221]
	v_lshlrev_b32_e32 v214, 16, v148
	v_and_b32_e32 v215, 0xffff0000, v148
	v_lshlrev_b32_e32 v216, 16, v149
	v_and_b32_e32 v217, 0xffff0000, v149
	v_lshlrev_b32_e32 v218, 16, v150
	v_and_b32_e32 v219, 0xffff0000, v150
	v_lshlrev_b32_e32 v220, 16, v151
	v_and_b32_e32 v221, 0xffff0000, v151
	v_max_f32_e32 v214, v214, v214
;     __device__ __forceinline__ void operator()(f32x4 (&acc)[2][2][4][2], const pg8::Unit& u, int wr, int wc, int fr, int fq) const {
;     ...
;                     const u32x4 ga = *(const u32x4*)(GA + o);
;                     float a8[8] = {bflo(ga.x), bfhi(ga.x), bflo(ga.y), bfhi(ga.y), bflo(ga.z), bfhi(ga.z), bflo(ga.w), bfhi(ga.w)};
; #pragma unroll
;                     for (int e = 0; e < 8; ++e) a8[e] = fmaxf(a8[e], 1e-30f);
;                     if (u.kind == 0) { const u32x4 gl = *(const u32x4*)(GL + o);
;                         const float l8[8] = {bflo(gl.x), bfhi(gl.x), bflo(gl.y), bfhi(gl.y), bflo(gl.z), bfhi(gl.z), bflo(gl.w), bfhi(gl.w)};
; #pragma unroll
;                         for (int e = 0; e < 4; ++e) { acc[ai][bj][m][0][e] *= l8[e] * __builtin_amdgcn_rcpf(a8[e]); acc[ai][bj][m][1][e] *= l8[4 + e] * __builtin_amdgcn_rcpf(a8[4 + e]); }
	v_max_f32_e32 v215, v215, v215
	v_max_f32_e32 v216, v216, v216
	v_max_f32_e32 v217, v217, v217
	v_max_f32_e32 v218, v218, v218
	v_max_f32_e32 v219, v219, v219
	v_max_f32_e32 v220, v220, v220
	v_max_f32_e32 v221, v221, v221
	v_max_f32_e32 v214, 0xda24260, v214
	v_max_f32_e32 v215, 0xda24260, v215
	v_max_f32_e32 v216, 0xda24260, v216
	v_max_f32_e32 v217, 0xda24260, v217
	v_max_f32_e32 v218, 0xda24260, v218
	v_max_f32_e32 v219, 0xda24260, v219
	v_max_f32_e32 v220, 0xda24260, v220
	v_max_f32_e32 v221, 0xda24260, v221
	v_rcp_f32_e32 v214, v214
	v_rcp_f32_e32 v215, v215
	v_rcp_f32_e32 v216, v216
	v_rcp_f32_e32 v217, v217
	v_rcp_f32_e32 v218, v218
	v_rcp_f32_e32 v219, v219
	v_rcp_f32_e32 v220, v220
	v_rcp_f32_e32 v221, v221
	v_lshlrev_b32_e32 v222, 16, v190
	v_and_b32_e32 v223, 0xffff0000, v190
	v_lshlrev_b32_e32 v224, 16, v191
	v_and_b32_e32 v225, 0xffff0000, v191
	v_lshlrev_b32_e32 v226, 16, v192
	v_and_b32_e32 v227, 0xffff0000, v192
	v_lshlrev_b32_e32 v228, 16, v193
	v_and_b32_e32 v229, 0xffff0000, v193
	v_pk_mul_f32 v[214:215], v[214:215], v[222:223]
	v_pk_mul_f32 v[216:217], v[216:217], v[224:225]
	v_pk_mul_f32 v[218:219], v[218:219], v[226:227]
	v_pk_mul_f32 v[220:221], v[220:221], v[228:229]
	v_pk_mul_f32 v[116:117], v[116:117], v[214:215]
	v_pk_mul_f32 v[118:119], v[118:119], v[216:217]
	v_pk_mul_f32 v[112:113], v[112:113], v[218:219]
	v_pk_mul_f32 v[114:115], v[114:115], v[220:221]
	v_lshlrev_b32_e32 v214, 16, v152
	v_and_b32_e32 v215, 0xffff0000, v152
	v_lshlrev_b32_e32 v216, 16, v153
	v_and_b32_e32 v217, 0xffff0000, v153
	v_lshlrev_b32_e32 v218, 16, v154
	v_and_b32_e32 v219, 0xffff0000, v154
	v_lshlrev_b32_e32 v220, 16, v155
	v_and_b32_e32 v221, 0xffff0000, v155
	v_max_f32_e32 v214, v214, v214
	v_max_f32_e32 v215, v215, v215
	v_max_f32_e32 v216, v216, v216
	v_max_f32_e32 v217, v217, v217
	v_max_f32_e32 v218, v218, v218
	v_max_f32_e32 v219, v219, v219
	v_max_f32_e32 v220, v220, v220
	v_max_f32_e32 v221, v221, v221
	v_max_f32_e32 v214, 0xda24260, v214
	v_max_f32_e32 v215, 0xda24260, v215
	v_max_f32_e32 v216, 0xda24260, v216
	v_max_f32_e32 v217, 0xda24260, v217
	v_max_f32_e32 v218, 0xda24260, v218
	v_max_f32_e32 v219, 0xda24260, v219
	v_max_f32_e32 v220, 0xda24260, v220
	v_max_f32_e32 v221, 0xda24260, v221
	v_rcp_f32_e32 v214, v214
	v_rcp_f32_e32 v215, v215
	v_rcp_f32_e32 v216, v216
	v_rcp_f32_e32 v217, v217
	v_rcp_f32_e32 v218, v218
	v_rcp_f32_e32 v219, v219
	v_rcp_f32_e32 v220, v220
	v_rcp_f32_e32 v221, v221
	v_lshlrev_b32_e32 v222, 16, v194
	v_and_b32_e32 v223, 0xffff0000, v194
	v_lshlrev_b32_e32 v224, 16, v195
	v_and_b32_e32 v225, 0xffff0000, v195
	v_lshlrev_b32_e32 v226, 16, v196
	v_and_b32_e32 v227, 0xffff0000, v196
	v_lshlrev_b32_e32 v228, 16, v197
	v_and_b32_e32 v229, 0xffff0000, v197
	v_pk_mul_f32 v[214:215], v[214:215], v[222:223]
	v_pk_mul_f32 v[216:217], v[216:217], v[224:225]
	v_pk_mul_f32 v[218:219], v[218:219], v[226:227]
	v_pk_mul_f32 v[220:221], v[220:221], v[228:229]
	v_pk_mul_f32 v[84:85], v[84:85], v[214:215]
	v_pk_mul_f32 v[86:87], v[86:87], v[216:217]
	v_pk_mul_f32 v[80:81], v[80:81], v[218:219]
	v_pk_mul_f32 v[82:83], v[82:83], v[220:221]
	v_lshlrev_b32_e32 v214, 16, v162
	v_and_b32_e32 v215, 0xffff0000, v162
	v_lshlrev_b32_e32 v216, 16, v163
	v_and_b32_e32 v217, 0xffff0000, v163
	v_lshlrev_b32_e32 v218, 16, v164
	v_and_b32_e32 v219, 0xffff0000, v164
	v_lshlrev_b32_e32 v220, 16, v165
	v_and_b32_e32 v221, 0xffff0000, v165
	v_max_f32_e32 v214, v214, v214
	v_max_f32_e32 v215, v215, v215
	v_max_f32_e32 v216, v216, v216
	v_max_f32_e32 v217, v217, v217
	v_max_f32_e32 v218, v218, v218
	v_max_f32_e32 v219, v219, v219
	v_max_f32_e32 v220, v220, v220
	v_max_f32_e32 v221, v221, v221
	v_max_f32_e32 v214, 0xda24260, v214
	v_max_f32_e32 v215, 0xda24260, v215
	v_max_f32_e32 v216, 0xda24260, v216
	v_max_f32_e32 v217, 0xda24260, v217
	v_max_f32_e32 v218, 0xda24260, v218
	v_max_f32_e32 v219, 0xda24260, v219
	v_max_f32_e32 v220, 0xda24260, v220
	v_max_f32_e32 v221, 0xda24260, v221
	v_rcp_f32_e32 v214, v214
	v_rcp_f32_e32 v215, v215
	v_rcp_f32_e32 v216, v216
	v_rcp_f32_e32 v217, v217
	v_rcp_f32_e32 v218, v218
	v_rcp_f32_e32 v219, v219
	v_rcp_f32_e32 v220, v220
	v_rcp_f32_e32 v221, v221
	v_lshlrev_b32_e32 v222, 16, v198
	v_and_b32_e32 v223, 0xffff0000, v198
	v_lshlrev_b32_e32 v224, 16, v199
	v_and_b32_e32 v225, 0xffff0000, v199
	v_lshlrev_b32_e32 v226, 16, v200
	v_and_b32_e32 v227, 0xffff0000, v200
	v_lshlrev_b32_e32 v228, 16, v201
	v_and_b32_e32 v229, 0xffff0000, v201
	v_pk_mul_f32 v[214:215], v[214:215], v[222:223]
	v_pk_mul_f32 v[216:217], v[216:217], v[224:225]
	v_pk_mul_f32 v[218:219], v[218:219], v[226:227]
	v_pk_mul_f32 v[220:221], v[220:221], v[228:229]
	v_pk_mul_f32 v[108:109], v[108:109], v[214:215]
	v_pk_mul_f32 v[110:111], v[110:111], v[216:217]
	v_pk_mul_f32 v[104:105], v[104:105], v[218:219]
	v_pk_mul_f32 v[106:107], v[106:107], v[220:221]
	v_lshlrev_b32_e32 v214, 16, v166
	v_and_b32_e32 v215, 0xffff0000, v166
	v_lshlrev_b32_e32 v216, 16, v167
	v_and_b32_e32 v217, 0xffff0000, v167
	v_lshlrev_b32_e32 v218, 16, v168
	v_and_b32_e32 v219, 0xffff0000, v168
	v_lshlrev_b32_e32 v220, 16, v169
	v_and_b32_e32 v221, 0xffff0000, v169
	v_max_f32_e32 v214, v214, v214
	v_max_f32_e32 v215, v215, v215
	v_max_f32_e32 v216, v216, v216
	v_max_f32_e32 v217, v217, v217
	v_max_f32_e32 v218, v218, v218
	v_max_f32_e32 v219, v219, v219
	v_max_f32_e32 v220, v220, v220
	v_max_f32_e32 v221, v221, v221
	v_max_f32_e32 v214, 0xda24260, v214
	v_max_f32_e32 v215, 0xda24260, v215
	v_max_f32_e32 v216, 0xda24260, v216
	v_max_f32_e32 v217, 0xda24260, v217
	v_max_f32_e32 v218, 0xda24260, v218
	v_max_f32_e32 v219, 0xda24260, v219
	v_max_f32_e32 v220, 0xda24260, v220
;     __device__ __forceinline__ void operator()(f32x4 (&acc)[2][2][4][2], const pg8::Unit& u, int wr, int wc, int fr, int fq) const {
;     ...
;                     const u32x4 ga = *(const u32x4*)(GA + o);
;                     float a8[8] = {bflo(ga.x), bfhi(ga.x), bflo(ga.y), bfhi(ga.y), bflo(ga.z), bfhi(ga.z), bflo(ga.w), bfhi(ga.w)};
; #pragma unroll
;                     for (int e = 0; e < 8; ++e) a8[e] = fmaxf(a8[e], 1e-30f);
;                     if (u.kind == 0) { const u32x4 gl = *(const u32x4*)(GL + o);
;                         const float l8[8] = {bflo(gl.x), bfhi(gl.x), bflo(gl.y), bfhi(gl.y), bflo(gl.z), bfhi(gl.z), bflo(gl.w), bfhi(gl.w)};
; #pragma unroll
;                         for (int e = 0; e < 4; ++e) { acc[ai][bj][m][0][e] *= l8[e] * __builtin_amdgcn_rcpf(a8[e]); acc[ai][bj][m][1][e] *= l8[4 + e] * __builtin_amdgcn_rcpf(a8[4 + e]); }
	v_max_f32_e32 v221, 0xda24260, v221
	v_rcp_f32_e32 v214, v214
	v_rcp_f32_e32 v215, v215
	v_rcp_f32_e32 v216, v216
	v_rcp_f32_e32 v217, v217
	v_rcp_f32_e32 v218, v218
	v_rcp_f32_e32 v219, v219
	v_rcp_f32_e32 v220, v220
	v_rcp_f32_e32 v221, v221
	v_lshlrev_b32_e32 v222, 16, v202
	v_and_b32_e32 v223, 0xffff0000, v202
	v_lshlrev_b32_e32 v224, 16, v203
	v_and_b32_e32 v225, 0xffff0000, v203
	v_lshlrev_b32_e32 v226, 16, v204
	v_and_b32_e32 v227, 0xffff0000, v204
	v_lshlrev_b32_e32 v228, 16, v205
	v_and_b32_e32 v229, 0xffff0000, v205
	v_pk_mul_f32 v[214:215], v[214:215], v[222:223]
	v_pk_mul_f32 v[216:217], v[216:217], v[224:225]
	v_pk_mul_f32 v[218:219], v[218:219], v[226:227]
	v_pk_mul_f32 v[220:221], v[220:221], v[228:229]
	v_pk_mul_f32 v[76:77], v[76:77], v[214:215]
	v_pk_mul_f32 v[78:79], v[78:79], v[216:217]
	v_pk_mul_f32 v[72:73], v[72:73], v[218:219]
	v_pk_mul_f32 v[74:75], v[74:75], v[220:221]
	v_lshlrev_b32_e32 v214, 16, v170
	v_and_b32_e32 v215, 0xffff0000, v170
	v_lshlrev_b32_e32 v216, 16, v171
	v_and_b32_e32 v217, 0xffff0000, v171
	v_lshlrev_b32_e32 v218, 16, v172
	v_and_b32_e32 v219, 0xffff0000, v172
	v_lshlrev_b32_e32 v220, 16, v173
	v_and_b32_e32 v221, 0xffff0000, v173
	v_max_f32_e32 v214, v214, v214
	v_max_f32_e32 v215, v215, v215
	v_max_f32_e32 v216, v216, v216
	v_max_f32_e32 v217, v217, v217
	v_max_f32_e32 v218, v218, v218
	v_max_f32_e32 v219, v219, v219
	v_max_f32_e32 v220, v220, v220
	v_max_f32_e32 v221, v221, v221
	v_max_f32_e32 v214, 0xda24260, v214
	v_max_f32_e32 v215, 0xda24260, v215
	v_max_f32_e32 v216, 0xda24260, v216
	v_max_f32_e32 v217, 0xda24260, v217
	v_max_f32_e32 v218, 0xda24260, v218
	v_max_f32_e32 v219, 0xda24260, v219
	v_max_f32_e32 v220, 0xda24260, v220
	v_max_f32_e32 v221, 0xda24260, v221
	v_rcp_f32_e32 v214, v214
	v_rcp_f32_e32 v215, v215
	v_rcp_f32_e32 v216, v216
	v_rcp_f32_e32 v217, v217
	v_rcp_f32_e32 v218, v218
	v_rcp_f32_e32 v219, v219
	v_rcp_f32_e32 v220, v220
	v_rcp_f32_e32 v221, v221
	v_lshlrev_b32_e32 v222, 16, v206
	v_and_b32_e32 v223, 0xffff0000, v206
	v_lshlrev_b32_e32 v224, 16, v207
	v_and_b32_e32 v225, 0xffff0000, v207
	v_lshlrev_b32_e32 v226, 16, v208
	v_and_b32_e32 v227, 0xffff0000, v208
	v_lshlrev_b32_e32 v228, 16, v209
	v_and_b32_e32 v229, 0xffff0000, v209
	v_pk_mul_f32 v[214:215], v[214:215], v[222:223]
	v_pk_mul_f32 v[216:217], v[216:217], v[224:225]
	v_pk_mul_f32 v[218:219], v[218:219], v[226:227]
	v_pk_mul_f32 v[220:221], v[220:221], v[228:229]
	v_pk_mul_f32 v[100:101], v[100:101], v[214:215]
	v_pk_mul_f32 v[102:103], v[102:103], v[216:217]
	v_pk_mul_f32 v[96:97], v[96:97], v[218:219]
	v_pk_mul_f32 v[98:99], v[98:99], v[220:221]
	v_lshlrev_b32_e32 v214, 16, v174
	v_and_b32_e32 v215, 0xffff0000, v174
	v_lshlrev_b32_e32 v216, 16, v175
	v_and_b32_e32 v217, 0xffff0000, v175
	v_lshlrev_b32_e32 v218, 16, v176
	v_and_b32_e32 v219, 0xffff0000, v176
	v_lshlrev_b32_e32 v220, 16, v177
	v_and_b32_e32 v221, 0xffff0000, v177
	v_max_f32_e32 v214, v214, v214
	v_max_f32_e32 v215, v215, v215
	v_max_f32_e32 v216, v216, v216
	v_max_f32_e32 v217, v217, v217
	v_max_f32_e32 v218, v218, v218
	v_max_f32_e32 v219, v219, v219
	v_max_f32_e32 v220, v220, v220
	v_max_f32_e32 v221, v221, v221
	v_max_f32_e32 v214, 0xda24260, v214
	v_max_f32_e32 v215, 0xda24260, v215
	v_max_f32_e32 v216, 0xda24260, v216
	v_max_f32_e32 v217, 0xda24260, v217
	v_max_f32_e32 v218, 0xda24260, v218
	v_max_f32_e32 v219, 0xda24260, v219
	v_max_f32_e32 v220, 0xda24260, v220
	v_max_f32_e32 v221, 0xda24260, v221
	v_rcp_f32_e32 v214, v214
	v_rcp_f32_e32 v215, v215
	v_rcp_f32_e32 v216, v216
	v_rcp_f32_e32 v217, v217
	v_rcp_f32_e32 v218, v218
	v_rcp_f32_e32 v219, v219
	v_rcp_f32_e32 v220, v220
	v_rcp_f32_e32 v221, v221
	v_lshlrev_b32_e32 v222, 16, v210
	v_and_b32_e32 v223, 0xffff0000, v210
	v_lshlrev_b32_e32 v224, 16, v211
	v_and_b32_e32 v225, 0xffff0000, v211
	v_lshlrev_b32_e32 v226, 16, v212
	v_and_b32_e32 v227, 0xffff0000, v212
	v_lshlrev_b32_e32 v228, 16, v213
	v_and_b32_e32 v229, 0xffff0000, v213
	v_pk_mul_f32 v[214:215], v[214:215], v[222:223]
	v_pk_mul_f32 v[216:217], v[216:217], v[224:225]
	v_pk_mul_f32 v[218:219], v[218:219], v[226:227]
	v_pk_mul_f32 v[220:221], v[220:221], v[228:229]
	v_pk_mul_f32 v[68:69], v[68:69], v[214:215]
	v_pk_mul_f32 v[70:71], v[70:71], v[216:217]
	v_pk_mul_f32 v[64:65], v[64:65], v[218:219]
	v_pk_mul_f32 v[66:67], v[66:67], v[220:221]
	global_load_dwordx4 v[140:143], v234, s[98:99]
	global_load_dwordx4 v[178:181], v234, s[100:101]
	global_load_dwordx4 v[144:147], v234, s[98:99] offset:256
	global_load_dwordx4 v[186:189], v234, s[100:101] offset:256
	s_add_u32 s98, s98, 0x8000
	s_addc_u32 s99, s99, 0
	s_add_u32 s100, s100, 0x8000
	s_addc_u32 s101, s101, 0
	global_load_dwordx4 v[148:151], v234, s[98:99]
	global_load_dwordx4 v[190:193], v234, s[100:101]
	global_load_dwordx4 v[152:155], v234, s[98:99] offset:256
	global_load_dwordx4 v[194:197], v234, s[100:101] offset:256
	s_add_u32 s98, s98, 0x8000
	s_addc_u32 s99, s99, 0
	s_add_u32 s100, s100, 0x8000
	s_addc_u32 s101, s101, 0
	global_load_dwordx4 v[162:165], v234, s[98:99]
	global_load_dwordx4 v[198:201], v234, s[100:101]
	global_load_dwordx4 v[166:169], v234, s[98:99] offset:256
	global_load_dwordx4 v[202:205], v234, s[100:101] offset:256
	s_add_u32 s98, s98, 0x8000
	s_addc_u32 s99, s99, 0
	s_add_u32 s100, s100, 0x8000
	s_addc_u32 s101, s101, 0
	global_load_dwordx4 v[170:173], v234, s[98:99]
	global_load_dwordx4 v[206:209], v234, s[100:101]
	global_load_dwordx4 v[174:177], v234, s[98:99] offset:256
	global_load_dwordx4 v[210:213], v234, s[100:101] offset:256
	s_add_u32 s98, s98, 0x28000
	s_addc_u32 s99, s99, 0
	s_add_u32 s100, s100, 0x28000
	s_addc_u32 s101, s101, 0
	s_waitcnt vmcnt(0)
;     __device__ __forceinline__ void operator()(f32x4 (&acc)[2][2][4][2], const pg8::Unit& u, int wr, int wc, int fr, int fq) const {
;     ...
;                     const u32x4 ga = *(const u32x4*)(GA + o);
;                     float a8[8] = {bflo(ga.x), bfhi(ga.x), bflo(ga.y), bfhi(ga.y), bflo(ga.z), bfhi(ga.z), bflo(ga.w), bfhi(ga.w)};
; #pragma unroll
;                     for (int e = 0; e < 8; ++e) a8[e] = fmaxf(a8[e], 1e-30f);
;                     if (u.kind == 0) { const u32x4 gl = *(const u32x4*)(GL + o);
;                         const float l8[8] = {bflo(gl.x), bfhi(gl.x), bflo(gl.y), bfhi(gl.y), bflo(gl.z), bfhi(gl.z), bflo(gl.w), bfhi(gl.w)};
; #pragma unroll
;                         for (int e = 0; e < 4; ++e) { acc[ai][bj][m][0][e] *= l8[e] * __builtin_amdgcn_rcpf(a8[e]); acc[ai][bj][m][1][e] *= l8[4 + e] * __builtin_amdgcn_rcpf(a8[4 + e]); }
	v_lshlrev_b32_e32 v214, 16, v140
	v_and_b32_e32 v215, 0xffff0000, v140
	v_lshlrev_b32_e32 v216, 16, v141
	v_and_b32_e32 v217, 0xffff0000, v141
	v_lshlrev_b32_e32 v218, 16, v142
	v_and_b32_e32 v219, 0xffff0000, v142
	v_lshlrev_b32_e32 v220, 16, v143
	v_and_b32_e32 v221, 0xffff0000, v143
	v_max_f32_e32 v214, v214, v214
	v_max_f32_e32 v215, v215, v215
	v_max_f32_e32 v216, v216, v216
	v_max_f32_e32 v217, v217, v217
	v_max_f32_e32 v218, v218, v218
	v_max_f32_e32 v219, v219, v219
	v_max_f32_e32 v220, v220, v220
	v_max_f32_e32 v221, v221, v221
	v_max_f32_e32 v214, 0xda24260, v214
	v_max_f32_e32 v215, 0xda24260, v215
	v_max_f32_e32 v216, 0xda24260, v216
	v_max_f32_e32 v217, 0xda24260, v217
	v_max_f32_e32 v218, 0xda24260, v218
	v_max_f32_e32 v219, 0xda24260, v219
	v_max_f32_e32 v220, 0xda24260, v220
	v_max_f32_e32 v221, 0xda24260, v221
	v_rcp_f32_e32 v214, v214
	v_rcp_f32_e32 v215, v215
	v_rcp_f32_e32 v216, v216
	v_rcp_f32_e32 v217, v217
	v_rcp_f32_e32 v218, v218
	v_rcp_f32_e32 v219, v219
	v_rcp_f32_e32 v220, v220
	v_rcp_f32_e32 v221, v221
	v_lshlrev_b32_e32 v222, 16, v178
	v_and_b32_e32 v223, 0xffff0000, v178
	v_lshlrev_b32_e32 v224, 16, v179
	v_and_b32_e32 v225, 0xffff0000, v179
	v_lshlrev_b32_e32 v226, 16, v180
	v_and_b32_e32 v227, 0xffff0000, v180
	v_lshlrev_b32_e32 v228, 16, v181
	v_and_b32_e32 v229, 0xffff0000, v181
	v_pk_mul_f32 v[214:215], v[214:215], v[222:223]
	v_pk_mul_f32 v[216:217], v[216:217], v[224:225]
	v_pk_mul_f32 v[218:219], v[218:219], v[226:227]
	v_pk_mul_f32 v[220:221], v[220:221], v[228:229]
	v_pk_mul_f32 v[60:61], v[60:61], v[214:215]
	v_pk_mul_f32 v[62:63], v[62:63], v[216:217]
	v_pk_mul_f32 v[56:57], v[56:57], v[218:219]
	v_pk_mul_f32 v[58:59], v[58:59], v[220:221]
	v_lshlrev_b32_e32 v214, 16, v144
	v_and_b32_e32 v215, 0xffff0000, v144
	v_lshlrev_b32_e32 v216, 16, v145
	v_and_b32_e32 v217, 0xffff0000, v145
	v_lshlrev_b32_e32 v218, 16, v146
	v_and_b32_e32 v219, 0xffff0000, v146
	v_lshlrev_b32_e32 v220, 16, v147
	v_and_b32_e32 v221, 0xffff0000, v147
	v_max_f32_e32 v214, v214, v214
	v_max_f32_e32 v215, v215, v215
	v_max_f32_e32 v216, v216, v216
	v_max_f32_e32 v217, v217, v217
	v_max_f32_e32 v218, v218, v218
	v_max_f32_e32 v219, v219, v219
	v_max_f32_e32 v220, v220, v220
	v_max_f32_e32 v221, v221, v221
	v_max_f32_e32 v214, 0xda24260, v214
	v_max_f32_e32 v215, 0xda24260, v215
	v_max_f32_e32 v216, 0xda24260, v216
	v_max_f32_e32 v217, 0xda24260, v217
	v_max_f32_e32 v218, 0xda24260, v218
	v_max_f32_e32 v219, 0xda24260, v219
	v_max_f32_e32 v220, 0xda24260, v220
	v_max_f32_e32 v221, 0xda24260, v221
	v_rcp_f32_e32 v214, v214
	v_rcp_f32_e32 v215, v215
	v_rcp_f32_e32 v216, v216
	v_rcp_f32_e32 v217, v217
	v_rcp_f32_e32 v218, v218
	v_rcp_f32_e32 v219, v219
	v_rcp_f32_e32 v220, v220
	v_rcp_f32_e32 v221, v221
	v_lshlrev_b32_e32 v222, 16, v186
	v_and_b32_e32 v223, 0xffff0000, v186
	v_lshlrev_b32_e32 v224, 16, v187
	v_and_b32_e32 v225, 0xffff0000, v187
	v_lshlrev_b32_e32 v226, 16, v188
	v_and_b32_e32 v227, 0xffff0000, v188
	v_lshlrev_b32_e32 v228, 16, v189
	v_and_b32_e32 v229, 0xffff0000, v189
	v_pk_mul_f32 v[214:215], v[214:215], v[222:223]
	v_pk_mul_f32 v[216:217], v[216:217], v[224:225]
	v_pk_mul_f32 v[218:219], v[218:219], v[226:227]
	v_pk_mul_f32 v[220:221], v[220:221], v[228:229]
	v_pk_mul_f32 v[28:29], v[28:29], v[214:215]
	v_pk_mul_f32 v[30:31], v[30:31], v[216:217]
	v_pk_mul_f32 v[24:25], v[24:25], v[218:219]
	v_pk_mul_f32 v[26:27], v[26:27], v[220:221]
	v_lshlrev_b32_e32 v214, 16, v148
	v_and_b32_e32 v215, 0xffff0000, v148
	v_lshlrev_b32_e32 v216, 16, v149
	v_and_b32_e32 v217, 0xffff0000, v149
	v_lshlrev_b32_e32 v218, 16, v150
	v_and_b32_e32 v219, 0xffff0000, v150
	v_lshlrev_b32_e32 v220, 16, v151
	v_and_b32_e32 v221, 0xffff0000, v151
	v_max_f32_e32 v214, v214, v214
	v_max_f32_e32 v215, v215, v215
	v_max_f32_e32 v216, v216, v216
	v_max_f32_e32 v217, v217, v217
	v_max_f32_e32 v218, v218, v218
	v_max_f32_e32 v219, v219, v219
	v_max_f32_e32 v220, v220, v220
	v_max_f32_e32 v221, v221, v221
	v_max_f32_e32 v214, 0xda24260, v214
	v_max_f32_e32 v215, 0xda24260, v215
	v_max_f32_e32 v216, 0xda24260, v216
	v_max_f32_e32 v217, 0xda24260, v217
	v_max_f32_e32 v218, 0xda24260, v218
	v_max_f32_e32 v219, 0xda24260, v219
	v_max_f32_e32 v220, 0xda24260, v220
	v_max_f32_e32 v221, 0xda24260, v221
	v_rcp_f32_e32 v214, v214
	v_rcp_f32_e32 v215, v215
	v_rcp_f32_e32 v216, v216
	v_rcp_f32_e32 v217, v217
	v_rcp_f32_e32 v218, v218
	v_rcp_f32_e32 v219, v219
	v_rcp_f32_e32 v220, v220
	v_rcp_f32_e32 v221, v221
	v_lshlrev_b32_e32 v222, 16, v190
	v_and_b32_e32 v223, 0xffff0000, v190
	v_lshlrev_b32_e32 v224, 16, v191
	v_and_b32_e32 v225, 0xffff0000, v191
	v_lshlrev_b32_e32 v226, 16, v192
	v_and_b32_e32 v227, 0xffff0000, v192
	v_lshlrev_b32_e32 v228, 16, v193
	v_and_b32_e32 v229, 0xffff0000, v193
	v_pk_mul_f32 v[214:215], v[214:215], v[222:223]
	v_pk_mul_f32 v[216:217], v[216:217], v[224:225]
	v_pk_mul_f32 v[218:219], v[218:219], v[226:227]
	v_pk_mul_f32 v[220:221], v[220:221], v[228:229]
	v_pk_mul_f32 v[52:53], v[52:53], v[214:215]
	v_pk_mul_f32 v[54:55], v[54:55], v[216:217]
	v_pk_mul_f32 v[48:49], v[48:49], v[218:219]
	v_pk_mul_f32 v[50:51], v[50:51], v[220:221]
	v_lshlrev_b32_e32 v214, 16, v152
	v_and_b32_e32 v215, 0xffff0000, v152
	v_lshlrev_b32_e32 v216, 16, v153
	v_and_b32_e32 v217, 0xffff0000, v153
	v_lshlrev_b32_e32 v218, 16, v154
	v_and_b32_e32 v219, 0xffff0000, v154
	v_lshlrev_b32_e32 v220, 16, v155
	v_and_b32_e32 v221, 0xffff0000, v155
	v_max_f32_e32 v214, v214, v214
	v_max_f32_e32 v215, v215, v215
	v_max_f32_e32 v216, v216, v216
	v_max_f32_e32 v217, v217, v217
	v_max_f32_e32 v218, v218, v218
	v_max_f32_e32 v219, v219, v219
	v_max_f32_e32 v220, v220, v220
;     __device__ __forceinline__ void operator()(f32x4 (&acc)[2][2][4][2], const pg8::Unit& u, int wr, int wc, int fr, int fq) const {
;     ...
;                     const u32x4 ga = *(const u32x4*)(GA + o);
;                     float a8[8] = {bflo(ga.x), bfhi(ga.x), bflo(ga.y), bfhi(ga.y), bflo(ga.z), bfhi(ga.z), bflo(ga.w), bfhi(ga.w)};
; #pragma unroll
;                     for (int e = 0; e < 8; ++e) a8[e] = fmaxf(a8[e], 1e-30f);
;                     if (u.kind == 0) { const u32x4 gl = *(const u32x4*)(GL + o);
;                         const float l8[8] = {bflo(gl.x), bfhi(gl.x), bflo(gl.y), bfhi(gl.y), bflo(gl.z), bfhi(gl.z), bflo(gl.w), bfhi(gl.w)};
; #pragma unroll
;                         for (int e = 0; e < 4; ++e) { acc[ai][bj][m][0][e] *= l8[e] * __builtin_amdgcn_rcpf(a8[e]); acc[ai][bj][m][1][e] *= l8[4 + e] * __builtin_amdgcn_rcpf(a8[4 + e]); }
	v_max_f32_e32 v221, v221, v221
	v_max_f32_e32 v214, 0xda24260, v214
	v_max_f32_e32 v215, 0xda24260, v215
	v_max_f32_e32 v216, 0xda24260, v216
	v_max_f32_e32 v217, 0xda24260, v217
	v_max_f32_e32 v218, 0xda24260, v218
	v_max_f32_e32 v219, 0xda24260, v219
	v_max_f32_e32 v220, 0xda24260, v220
	v_max_f32_e32 v221, 0xda24260, v221
	v_rcp_f32_e32 v214, v214
	v_rcp_f32_e32 v215, v215
	v_rcp_f32_e32 v216, v216
	v_rcp_f32_e32 v217, v217
	v_rcp_f32_e32 v218, v218
	v_rcp_f32_e32 v219, v219
	v_rcp_f32_e32 v220, v220
	v_rcp_f32_e32 v221, v221
	v_lshlrev_b32_e32 v222, 16, v194
	v_and_b32_e32 v223, 0xffff0000, v194
	v_lshlrev_b32_e32 v224, 16, v195
	v_and_b32_e32 v225, 0xffff0000, v195
	v_lshlrev_b32_e32 v226, 16, v196
	v_and_b32_e32 v227, 0xffff0000, v196
	v_lshlrev_b32_e32 v228, 16, v197
	v_and_b32_e32 v229, 0xffff0000, v197
	v_pk_mul_f32 v[214:215], v[214:215], v[222:223]
	v_pk_mul_f32 v[216:217], v[216:217], v[224:225]
	v_pk_mul_f32 v[218:219], v[218:219], v[226:227]
	v_pk_mul_f32 v[220:221], v[220:221], v[228:229]
	v_pk_mul_f32 v[20:21], v[20:21], v[214:215]
	v_pk_mul_f32 v[22:23], v[22:23], v[216:217]
	v_pk_mul_f32 v[16:17], v[16:17], v[218:219]
	v_pk_mul_f32 v[18:19], v[18:19], v[220:221]
	v_lshlrev_b32_e32 v214, 16, v162
	v_and_b32_e32 v215, 0xffff0000, v162
	v_lshlrev_b32_e32 v216, 16, v163
	v_and_b32_e32 v217, 0xffff0000, v163
	v_lshlrev_b32_e32 v218, 16, v164
	v_and_b32_e32 v219, 0xffff0000, v164
	v_lshlrev_b32_e32 v220, 16, v165
	v_and_b32_e32 v221, 0xffff0000, v165
	v_max_f32_e32 v214, v214, v214
	v_max_f32_e32 v215, v215, v215
	v_max_f32_e32 v216, v216, v216
	v_max_f32_e32 v217, v217, v217
	v_max_f32_e32 v218, v218, v218
	v_max_f32_e32 v219, v219, v219
	v_max_f32_e32 v220, v220, v220
	v_max_f32_e32 v221, v221, v221
	v_max_f32_e32 v214, 0xda24260, v214
	v_max_f32_e32 v215, 0xda24260, v215
	v_max_f32_e32 v216, 0xda24260, v216
	v_max_f32_e32 v217, 0xda24260, v217
	v_max_f32_e32 v218, 0xda24260, v218
	v_max_f32_e32 v219, 0xda24260, v219
	v_max_f32_e32 v220, 0xda24260, v220
	v_max_f32_e32 v221, 0xda24260, v221
	v_rcp_f32_e32 v214, v214
	v_rcp_f32_e32 v215, v215
	v_rcp_f32_e32 v216, v216
	v_rcp_f32_e32 v217, v217
	v_rcp_f32_e32 v218, v218
	v_rcp_f32_e32 v219, v219
	v_rcp_f32_e32 v220, v220
	v_rcp_f32_e32 v221, v221
	v_lshlrev_b32_e32 v222, 16, v198
	v_and_b32_e32 v223, 0xffff0000, v198
	v_lshlrev_b32_e32 v224, 16, v199
	v_and_b32_e32 v225, 0xffff0000, v199
	v_lshlrev_b32_e32 v226, 16, v200
	v_and_b32_e32 v227, 0xffff0000, v200
	v_lshlrev_b32_e32 v228, 16, v201
	v_and_b32_e32 v229, 0xffff0000, v201
	v_pk_mul_f32 v[214:215], v[214:215], v[222:223]
	v_pk_mul_f32 v[216:217], v[216:217], v[224:225]
	v_pk_mul_f32 v[218:219], v[218:219], v[226:227]
	v_pk_mul_f32 v[220:221], v[220:221], v[228:229]
	v_pk_mul_f32 v[44:45], v[44:45], v[214:215]
	v_pk_mul_f32 v[46:47], v[46:47], v[216:217]
	v_pk_mul_f32 v[40:41], v[40:41], v[218:219]
	v_pk_mul_f32 v[42:43], v[42:43], v[220:221]
	v_lshlrev_b32_e32 v214, 16, v166
	v_and_b32_e32 v215, 0xffff0000, v166
	v_lshlrev_b32_e32 v216, 16, v167
	v_and_b32_e32 v217, 0xffff0000, v167
	v_lshlrev_b32_e32 v218, 16, v168
	v_and_b32_e32 v219, 0xffff0000, v168
	v_lshlrev_b32_e32 v220, 16, v169
	v_and_b32_e32 v221, 0xffff0000, v169
	v_max_f32_e32 v214, v214, v214
	v_max_f32_e32 v215, v215, v215
	v_max_f32_e32 v216, v216, v216
	v_max_f32_e32 v217, v217, v217
	v_max_f32_e32 v218, v218, v218
	v_max_f32_e32 v219, v219, v219
	v_max_f32_e32 v220, v220, v220
	v_max_f32_e32 v221, v221, v221
	v_max_f32_e32 v214, 0xda24260, v214
	v_max_f32_e32 v215, 0xda24260, v215
	v_max_f32_e32 v216, 0xda24260, v216
	v_max_f32_e32 v217, 0xda24260, v217
	v_max_f32_e32 v218, 0xda24260, v218
	v_max_f32_e32 v219, 0xda24260, v219
	v_max_f32_e32 v220, 0xda24260, v220
	v_max_f32_e32 v221, 0xda24260, v221
	v_rcp_f32_e32 v214, v214
	v_rcp_f32_e32 v215, v215
	v_rcp_f32_e32 v216, v216
	v_rcp_f32_e32 v217, v217
	v_rcp_f32_e32 v218, v218
	v_rcp_f32_e32 v219, v219
	v_rcp_f32_e32 v220, v220
	v_rcp_f32_e32 v221, v221
	v_lshlrev_b32_e32 v222, 16, v202
	v_and_b32_e32 v223, 0xffff0000, v202
	v_lshlrev_b32_e32 v224, 16, v203
	v_and_b32_e32 v225, 0xffff0000, v203
	v_lshlrev_b32_e32 v226, 16, v204
	v_and_b32_e32 v227, 0xffff0000, v204
	v_lshlrev_b32_e32 v228, 16, v205
	v_and_b32_e32 v229, 0xffff0000, v205
	v_pk_mul_f32 v[214:215], v[214:215], v[222:223]
	v_pk_mul_f32 v[216:217], v[216:217], v[224:225]
	v_pk_mul_f32 v[218:219], v[218:219], v[226:227]
	v_pk_mul_f32 v[220:221], v[220:221], v[228:229]
	v_pk_mul_f32 v[12:13], v[12:13], v[214:215]
	v_pk_mul_f32 v[14:15], v[14:15], v[216:217]
	v_pk_mul_f32 v[8:9], v[8:9], v[218:219]
	v_pk_mul_f32 v[10:11], v[10:11], v[220:221]
	v_lshlrev_b32_e32 v214, 16, v170
	v_and_b32_e32 v215, 0xffff0000, v170
	v_lshlrev_b32_e32 v216, 16, v171
	v_and_b32_e32 v217, 0xffff0000, v171
	v_lshlrev_b32_e32 v218, 16, v172
	v_and_b32_e32 v219, 0xffff0000, v172
	v_lshlrev_b32_e32 v220, 16, v173
	v_and_b32_e32 v221, 0xffff0000, v173
	v_max_f32_e32 v214, v214, v214
	v_max_f32_e32 v215, v215, v215
	v_max_f32_e32 v216, v216, v216
	v_max_f32_e32 v217, v217, v217
	v_max_f32_e32 v218, v218, v218
	v_max_f32_e32 v219, v219, v219
	v_max_f32_e32 v220, v220, v220
	v_max_f32_e32 v221, v221, v221
	v_max_f32_e32 v214, 0xda24260, v214
	v_max_f32_e32 v215, 0xda24260, v215
	v_max_f32_e32 v216, 0xda24260, v216
	v_max_f32_e32 v217, 0xda24260, v217
	v_max_f32_e32 v218, 0xda24260, v218
	v_max_f32_e32 v219, 0xda24260, v219
	v_max_f32_e32 v220, 0xda24260, v220
	v_max_f32_e32 v221, 0xda24260, v221
	v_rcp_f32_e32 v214, v214
	v_rcp_f32_e32 v215, v215
	v_rcp_f32_e32 v216, v216
	v_rcp_f32_e32 v217, v217
	v_rcp_f32_e32 v218, v218
	v_rcp_f32_e32 v219, v219
	v_rcp_f32_e32 v220, v220
; __device__ __forceinline__ u32x4 pack8(f32x4 a, f32x4 b) { u32x4 w; w.x = cvt_pk(a[0], a[1]); w.y = cvt_pk(a[2], a[3]); w.z = cvt_pk(b[0], b[1]); w.w = cvt_pk(b[2], b[3]); return w; }
;     __device__ __forceinline__ void operator()(f32x4 (&acc)[2][2][4][2], const pg8::Unit& u, int wr, int wc, int fr, int fq) const {
;     ...
;                     const u32x4 ga = *(const u32x4*)(GA + o);
;                     float a8[8] = {bflo(ga.x), bfhi(ga.x), bflo(ga.y), bfhi(ga.y), bflo(ga.z), bfhi(ga.z), bflo(ga.w), bfhi(ga.w)};
; #pragma unroll
;                     for (int e = 0; e < 8; ++e) a8[e] = fmaxf(a8[e], 1e-30f);
;                     if (u.kind == 0) { const u32x4 gl = *(const u32x4*)(GL + o);
;                         const float l8[8] = {bflo(gl.x), bfhi(gl.x), bflo(gl.y), bfhi(gl.y), bflo(gl.z), bfhi(gl.z), bflo(gl.w), bfhi(gl.w)};
; #pragma unroll
;                         for (int e = 0; e < 4; ++e) { acc[ai][bj][m][0][e] *= l8[e] * __builtin_amdgcn_rcpf(a8[e]); acc[ai][bj][m][1][e] *= l8[4 + e] * __builtin_amdgcn_rcpf(a8[4 + e]); }
;                     } else { f32x4 v0 = acc[ai][bj][m][0], v1 = acc[ai][bj][m][1];
; #pragma unroll
;                         for (int e = 0; e < 4; ++e) { v0[e] *= a8[e]; v1[e] *= a8[4 + e]; }
;                         *(u32x4*)(MG + o) = pack8(v0, v1); } } }
	v_rcp_f32_e32 v221, v221
	v_lshlrev_b32_e32 v222, 16, v206
	v_and_b32_e32 v223, 0xffff0000, v206
	v_lshlrev_b32_e32 v224, 16, v207
	v_and_b32_e32 v225, 0xffff0000, v207
	v_lshlrev_b32_e32 v226, 16, v208
	v_and_b32_e32 v227, 0xffff0000, v208
	v_lshlrev_b32_e32 v228, 16, v209
	v_and_b32_e32 v229, 0xffff0000, v209
	v_pk_mul_f32 v[214:215], v[214:215], v[222:223]
	v_pk_mul_f32 v[216:217], v[216:217], v[224:225]
	v_pk_mul_f32 v[218:219], v[218:219], v[226:227]
	v_pk_mul_f32 v[220:221], v[220:221], v[228:229]
	v_pk_mul_f32 v[36:37], v[36:37], v[214:215]
	v_pk_mul_f32 v[38:39], v[38:39], v[216:217]
	v_pk_mul_f32 v[32:33], v[32:33], v[218:219]
	v_pk_mul_f32 v[34:35], v[34:35], v[220:221]
	v_lshlrev_b32_e32 v214, 16, v174
	v_and_b32_e32 v215, 0xffff0000, v174
	v_lshlrev_b32_e32 v216, 16, v175
	v_and_b32_e32 v217, 0xffff0000, v175
	v_lshlrev_b32_e32 v218, 16, v176
	v_and_b32_e32 v219, 0xffff0000, v176
	v_lshlrev_b32_e32 v220, 16, v177
	v_and_b32_e32 v221, 0xffff0000, v177
	v_max_f32_e32 v214, v214, v214
	v_max_f32_e32 v215, v215, v215
	v_max_f32_e32 v216, v216, v216
	v_max_f32_e32 v217, v217, v217
	v_max_f32_e32 v218, v218, v218
	v_max_f32_e32 v219, v219, v219
	v_max_f32_e32 v220, v220, v220
	v_max_f32_e32 v221, v221, v221
	v_max_f32_e32 v214, 0xda24260, v214
	v_max_f32_e32 v215, 0xda24260, v215
	v_max_f32_e32 v216, 0xda24260, v216
	v_max_f32_e32 v217, 0xda24260, v217
	v_max_f32_e32 v218, 0xda24260, v218
	v_max_f32_e32 v219, 0xda24260, v219
	v_max_f32_e32 v220, 0xda24260, v220
	v_max_f32_e32 v221, 0xda24260, v221
	v_rcp_f32_e32 v214, v214
	v_rcp_f32_e32 v215, v215
	v_rcp_f32_e32 v216, v216
	v_rcp_f32_e32 v217, v217
	v_rcp_f32_e32 v218, v218
	v_rcp_f32_e32 v219, v219
	v_rcp_f32_e32 v220, v220
	v_rcp_f32_e32 v221, v221
	v_lshlrev_b32_e32 v222, 16, v210
	v_and_b32_e32 v223, 0xffff0000, v210
	v_lshlrev_b32_e32 v224, 16, v211
	v_and_b32_e32 v225, 0xffff0000, v211
	v_lshlrev_b32_e32 v226, 16, v212
	v_and_b32_e32 v227, 0xffff0000, v212
	v_lshlrev_b32_e32 v228, 16, v213
	v_and_b32_e32 v229, 0xffff0000, v213
	v_pk_mul_f32 v[214:215], v[214:215], v[222:223]
	v_pk_mul_f32 v[216:217], v[216:217], v[224:225]
	v_pk_mul_f32 v[218:219], v[218:219], v[226:227]
	v_pk_mul_f32 v[220:221], v[220:221], v[228:229]
	v_pk_mul_f32 v[4:5], v[4:5], v[214:215]
	v_pk_mul_f32 v[6:7], v[6:7], v[216:217]
	v_pk_mul_f32 v[0:1], v[0:1], v[218:219]
	v_pk_mul_f32 v[2:3], v[2:3], v[220:221]
	s_mov_b64 s[4:5], -1
	s_branch .Lbr_done
.Lbr_kind1:
	s_mov_b64 s[100:101], s[88:89]
	global_load_dwordx4 v[140:143], v234, s[98:99]
	global_load_dwordx4 v[144:147], v234, s[98:99] offset:256
	s_add_u32 s98, s98, 0x8000
	s_addc_u32 s99, s99, 0
	global_load_dwordx4 v[148:151], v234, s[98:99]
	global_load_dwordx4 v[152:155], v234, s[98:99] offset:256
	s_add_u32 s98, s98, 0x8000
	s_addc_u32 s99, s99, 0
	global_load_dwordx4 v[162:165], v234, s[98:99]
	global_load_dwordx4 v[166:169], v234, s[98:99] offset:256
	s_add_u32 s98, s98, 0x8000
	s_addc_u32 s99, s99, 0
	global_load_dwordx4 v[170:173], v234, s[98:99]
	global_load_dwordx4 v[174:177], v234, s[98:99] offset:256
	s_add_u32 s98, s98, 0x28000
	s_addc_u32 s99, s99, 0
	global_load_dwordx4 v[178:181], v234, s[98:99]
	global_load_dwordx4 v[186:189], v234, s[98:99] offset:256
	s_add_u32 s98, s98, 0x8000
	s_addc_u32 s99, s99, 0
	global_load_dwordx4 v[190:193], v234, s[98:99]
	global_load_dwordx4 v[194:197], v234, s[98:99] offset:256
	s_add_u32 s98, s98, 0x8000
	s_addc_u32 s99, s99, 0
	global_load_dwordx4 v[198:201], v234, s[98:99]
	global_load_dwordx4 v[202:205], v234, s[98:99] offset:256
	s_add_u32 s98, s98, 0x8000
	s_addc_u32 s99, s99, 0
	global_load_dwordx4 v[206:209], v234, s[98:99]
	global_load_dwordx4 v[210:213], v234, s[98:99] offset:256
	s_add_u32 s98, s98, 0x28000
	s_addc_u32 s99, s99, 0
	s_waitcnt vmcnt(0)
	v_lshlrev_b32_e32 v214, 16, v140
	v_and_b32_e32 v215, 0xffff0000, v140
	v_lshlrev_b32_e32 v216, 16, v141
	v_and_b32_e32 v217, 0xffff0000, v141
	v_lshlrev_b32_e32 v218, 16, v142
	v_and_b32_e32 v219, 0xffff0000, v142
	v_lshlrev_b32_e32 v220, 16, v143
	v_and_b32_e32 v221, 0xffff0000, v143
	v_max_f32_e32 v214, v214, v214
	v_max_f32_e32 v215, v215, v215
	v_max_f32_e32 v216, v216, v216
	v_max_f32_e32 v217, v217, v217
	v_max_f32_e32 v218, v218, v218
	v_max_f32_e32 v219, v219, v219
	v_max_f32_e32 v220, v220, v220
	v_max_f32_e32 v221, v221, v221
	v_max_f32_e32 v214, 0xda24260, v214
	v_max_f32_e32 v215, 0xda24260, v215
	v_max_f32_e32 v216, 0xda24260, v216
	v_max_f32_e32 v217, 0xda24260, v217
	v_max_f32_e32 v218, 0xda24260, v218
	v_max_f32_e32 v219, 0xda24260, v219
	v_max_f32_e32 v220, 0xda24260, v220
	v_max_f32_e32 v221, 0xda24260, v221
	v_pk_mul_f32 v[222:223], v[124:125], v[214:215]
	v_pk_mul_f32 v[224:225], v[126:127], v[216:217]
	v_pk_mul_f32 v[226:227], v[120:121], v[218:219]
	v_pk_mul_f32 v[228:229], v[122:123], v[220:221]
	v_cvt_pk_bf16_f32 v230, v222, v223
	v_cvt_pk_bf16_f32 v231, v224, v225
	v_cvt_pk_bf16_f32 v232, v226, v227
	v_cvt_pk_bf16_f32 v233, v228, v229
	global_store_dwordx4 v234, v[230:233], s[100:101]
	v_lshlrev_b32_e32 v214, 16, v144
	v_and_b32_e32 v215, 0xffff0000, v144
	v_lshlrev_b32_e32 v216, 16, v145
	v_and_b32_e32 v217, 0xffff0000, v145
	v_lshlrev_b32_e32 v218, 16, v146
	v_and_b32_e32 v219, 0xffff0000, v146
	v_lshlrev_b32_e32 v220, 16, v147
	v_and_b32_e32 v221, 0xffff0000, v147
	v_max_f32_e32 v214, v214, v214
	v_max_f32_e32 v215, v215, v215
	v_max_f32_e32 v216, v216, v216
	v_max_f32_e32 v217, v217, v217
	v_max_f32_e32 v218, v218, v218
	v_max_f32_e32 v219, v219, v219
	v_max_f32_e32 v220, v220, v220
	v_max_f32_e32 v221, v221, v221
	v_max_f32_e32 v214, 0xda24260, v214
	v_max_f32_e32 v215, 0xda24260, v215
	v_max_f32_e32 v216, 0xda24260, v216
; __device__ __forceinline__ u32x4 pack8(f32x4 a, f32x4 b) { u32x4 w; w.x = cvt_pk(a[0], a[1]); w.y = cvt_pk(a[2], a[3]); w.z = cvt_pk(b[0], b[1]); w.w = cvt_pk(b[2], b[3]); return w; }
;     __device__ __forceinline__ void operator()(f32x4 (&acc)[2][2][4][2], const pg8::Unit& u, int wr, int wc, int fr, int fq) const {
;     ...
;                     const u32x4 ga = *(const u32x4*)(GA + o);
;                     float a8[8] = {bflo(ga.x), bfhi(ga.x), bflo(ga.y), bfhi(ga.y), bflo(ga.z), bfhi(ga.z), bflo(ga.w), bfhi(ga.w)};
; #pragma unroll
;                     for (int e = 0; e < 8; ++e) a8[e] = fmaxf(a8[e], 1e-30f);
;     ...
;                     } else { f32x4 v0 = acc[ai][bj][m][0], v1 = acc[ai][bj][m][1];
; #pragma unroll
;                         for (int e = 0; e < 4; ++e) { v0[e] *= a8[e]; v1[e] *= a8[4 + e]; }
;                         *(u32x4*)(MG + o) = pack8(v0, v1); } } }
	v_max_f32_e32 v217, 0xda24260, v217
	v_max_f32_e32 v218, 0xda24260, v218
	v_max_f32_e32 v219, 0xda24260, v219
	v_max_f32_e32 v220, 0xda24260, v220
	v_max_f32_e32 v221, 0xda24260, v221
	v_pk_mul_f32 v[222:223], v[92:93], v[214:215]
	v_pk_mul_f32 v[224:225], v[94:95], v[216:217]
	v_pk_mul_f32 v[226:227], v[88:89], v[218:219]
	v_pk_mul_f32 v[228:229], v[90:91], v[220:221]
	v_cvt_pk_bf16_f32 v230, v222, v223
	v_cvt_pk_bf16_f32 v231, v224, v225
	v_cvt_pk_bf16_f32 v232, v226, v227
	v_cvt_pk_bf16_f32 v233, v228, v229
	global_store_dwordx4 v234, v[230:233], s[100:101] offset:256
	s_add_u32 s100, s100, 0x8000
	s_addc_u32 s101, s101, 0
	v_lshlrev_b32_e32 v214, 16, v148
	v_and_b32_e32 v215, 0xffff0000, v148
	v_lshlrev_b32_e32 v216, 16, v149
	v_and_b32_e32 v217, 0xffff0000, v149
	v_lshlrev_b32_e32 v218, 16, v150
	v_and_b32_e32 v219, 0xffff0000, v150
	v_lshlrev_b32_e32 v220, 16, v151
	v_and_b32_e32 v221, 0xffff0000, v151
	v_max_f32_e32 v214, v214, v214
	v_max_f32_e32 v215, v215, v215
	v_max_f32_e32 v216, v216, v216
	v_max_f32_e32 v217, v217, v217
	v_max_f32_e32 v218, v218, v218
	v_max_f32_e32 v219, v219, v219
	v_max_f32_e32 v220, v220, v220
	v_max_f32_e32 v221, v221, v221
	v_max_f32_e32 v214, 0xda24260, v214
	v_max_f32_e32 v215, 0xda24260, v215
	v_max_f32_e32 v216, 0xda24260, v216
	v_max_f32_e32 v217, 0xda24260, v217
	v_max_f32_e32 v218, 0xda24260, v218
	v_max_f32_e32 v219, 0xda24260, v219
	v_max_f32_e32 v220, 0xda24260, v220
	v_max_f32_e32 v221, 0xda24260, v221
	v_pk_mul_f32 v[222:223], v[116:117], v[214:215]
	v_pk_mul_f32 v[224:225], v[118:119], v[216:217]
	v_pk_mul_f32 v[226:227], v[112:113], v[218:219]
	v_pk_mul_f32 v[228:229], v[114:115], v[220:221]
	v_cvt_pk_bf16_f32 v230, v222, v223
	v_cvt_pk_bf16_f32 v231, v224, v225
	v_cvt_pk_bf16_f32 v232, v226, v227
	v_cvt_pk_bf16_f32 v233, v228, v229
	global_store_dwordx4 v234, v[230:233], s[100:101]
	v_lshlrev_b32_e32 v214, 16, v152
	v_and_b32_e32 v215, 0xffff0000, v152
	v_lshlrev_b32_e32 v216, 16, v153
	v_and_b32_e32 v217, 0xffff0000, v153
	v_lshlrev_b32_e32 v218, 16, v154
	v_and_b32_e32 v219, 0xffff0000, v154
	v_lshlrev_b32_e32 v220, 16, v155
	v_and_b32_e32 v221, 0xffff0000, v155
	v_max_f32_e32 v214, v214, v214
	v_max_f32_e32 v215, v215, v215
	v_max_f32_e32 v216, v216, v216
	v_max_f32_e32 v217, v217, v217
	v_max_f32_e32 v218, v218, v218
	v_max_f32_e32 v219, v219, v219
	v_max_f32_e32 v220, v220, v220
	v_max_f32_e32 v221, v221, v221
	v_max_f32_e32 v214, 0xda24260, v214
	v_max_f32_e32 v215, 0xda24260, v215
	v_max_f32_e32 v216, 0xda24260, v216
	v_max_f32_e32 v217, 0xda24260, v217
	v_max_f32_e32 v218, 0xda24260, v218
	v_max_f32_e32 v219, 0xda24260, v219
	v_max_f32_e32 v220, 0xda24260, v220
	v_max_f32_e32 v221, 0xda24260, v221
	v_pk_mul_f32 v[222:223], v[84:85], v[214:215]
	v_pk_mul_f32 v[224:225], v[86:87], v[216:217]
	v_pk_mul_f32 v[226:227], v[80:81], v[218:219]
	v_pk_mul_f32 v[228:229], v[82:83], v[220:221]
	v_cvt_pk_bf16_f32 v230, v222, v223
	v_cvt_pk_bf16_f32 v231, v224, v225
	v_cvt_pk_bf16_f32 v232, v226, v227
	v_cvt_pk_bf16_f32 v233, v228, v229
	global_store_dwordx4 v234, v[230:233], s[100:101] offset:256
	s_add_u32 s100, s100, 0x8000
	s_addc_u32 s101, s101, 0
	v_lshlrev_b32_e32 v214, 16, v162
	v_and_b32_e32 v215, 0xffff0000, v162
	v_lshlrev_b32_e32 v216, 16, v163
	v_and_b32_e32 v217, 0xffff0000, v163
	v_lshlrev_b32_e32 v218, 16, v164
	v_and_b32_e32 v219, 0xffff0000, v164
	v_lshlrev_b32_e32 v220, 16, v165
	v_and_b32_e32 v221, 0xffff0000, v165
	v_max_f32_e32 v214, v214, v214
	v_max_f32_e32 v215, v215, v215
	v_max_f32_e32 v216, v216, v216
	v_max_f32_e32 v217, v217, v217
	v_max_f32_e32 v218, v218, v218
	v_max_f32_e32 v219, v219, v219
	v_max_f32_e32 v220, v220, v220
	v_max_f32_e32 v221, v221, v221
	v_max_f32_e32 v214, 0xda24260, v214
	v_max_f32_e32 v215, 0xda24260, v215
	v_max_f32_e32 v216, 0xda24260, v216
	v_max_f32_e32 v217, 0xda24260, v217
	v_max_f32_e32 v218, 0xda24260, v218
	v_max_f32_e32 v219, 0xda24260, v219
	v_max_f32_e32 v220, 0xda24260, v220
	v_max_f32_e32 v221, 0xda24260, v221
	v_pk_mul_f32 v[222:223], v[108:109], v[214:215]
	v_pk_mul_f32 v[224:225], v[110:111], v[216:217]
	v_pk_mul_f32 v[226:227], v[104:105], v[218:219]
	v_pk_mul_f32 v[228:229], v[106:107], v[220:221]
	v_cvt_pk_bf16_f32 v230, v222, v223
	v_cvt_pk_bf16_f32 v231, v224, v225
	v_cvt_pk_bf16_f32 v232, v226, v227
	v_cvt_pk_bf16_f32 v233, v228, v229
	global_store_dwordx4 v234, v[230:233], s[100:101]
	v_lshlrev_b32_e32 v214, 16, v166
	v_and_b32_e32 v215, 0xffff0000, v166
	v_lshlrev_b32_e32 v216, 16, v167
	v_and_b32_e32 v217, 0xffff0000, v167
	v_lshlrev_b32_e32 v218, 16, v168
	v_and_b32_e32 v219, 0xffff0000, v168
	v_lshlrev_b32_e32 v220, 16, v169
	v_and_b32_e32 v221, 0xffff0000, v169
	v_max_f32_e32 v214, v214, v214
	v_max_f32_e32 v215, v215, v215
	v_max_f32_e32 v216, v216, v216
	v_max_f32_e32 v217, v217, v217
	v_max_f32_e32 v218, v218, v218
	v_max_f32_e32 v219, v219, v219
	v_max_f32_e32 v220, v220, v220
	v_max_f32_e32 v221, v221, v221
	v_max_f32_e32 v214, 0xda24260, v214
	v_max_f32_e32 v215, 0xda24260, v215
	v_max_f32_e32 v216, 0xda24260, v216
	v_max_f32_e32 v217, 0xda24260, v217
	v_max_f32_e32 v218, 0xda24260, v218
	v_max_f32_e32 v219, 0xda24260, v219
	v_max_f32_e32 v220, 0xda24260, v220
	v_max_f32_e32 v221, 0xda24260, v221
	v_pk_mul_f32 v[222:223], v[76:77], v[214:215]
	v_pk_mul_f32 v[224:225], v[78:79], v[216:217]
	v_pk_mul_f32 v[226:227], v[72:73], v[218:219]
	v_pk_mul_f32 v[228:229], v[74:75], v[220:221]
	v_cvt_pk_bf16_f32 v230, v222, v223
	v_cvt_pk_bf16_f32 v231, v224, v225
	v_cvt_pk_bf16_f32 v232, v226, v227
	v_cvt_pk_bf16_f32 v233, v228, v229
	global_store_dwordx4 v234, v[230:233], s[100:101] offset:256
	s_add_u32 s100, s100, 0x8000
; __device__ __forceinline__ u32x4 pack8(f32x4 a, f32x4 b) { u32x4 w; w.x = cvt_pk(a[0], a[1]); w.y = cvt_pk(a[2], a[3]); w.z = cvt_pk(b[0], b[1]); w.w = cvt_pk(b[2], b[3]); return w; }
;     __device__ __forceinline__ void operator()(f32x4 (&acc)[2][2][4][2], const pg8::Unit& u, int wr, int wc, int fr, int fq) const {
;     ...
;                     const u32x4 ga = *(const u32x4*)(GA + o);
;                     float a8[8] = {bflo(ga.x), bfhi(ga.x), bflo(ga.y), bfhi(ga.y), bflo(ga.z), bfhi(ga.z), bflo(ga.w), bfhi(ga.w)};
; #pragma unroll
;                     for (int e = 0; e < 8; ++e) a8[e] = fmaxf(a8[e], 1e-30f);
;     ...
;                     } else { f32x4 v0 = acc[ai][bj][m][0], v1 = acc[ai][bj][m][1];
; #pragma unroll
;                         for (int e = 0; e < 4; ++e) { v0[e] *= a8[e]; v1[e] *= a8[4 + e]; }
;                         *(u32x4*)(MG + o) = pack8(v0, v1); } } }
	s_addc_u32 s101, s101, 0
	v_lshlrev_b32_e32 v214, 16, v170
	v_and_b32_e32 v215, 0xffff0000, v170
	v_lshlrev_b32_e32 v216, 16, v171
	v_and_b32_e32 v217, 0xffff0000, v171
	v_lshlrev_b32_e32 v218, 16, v172
	v_and_b32_e32 v219, 0xffff0000, v172
	v_lshlrev_b32_e32 v220, 16, v173
	v_and_b32_e32 v221, 0xffff0000, v173
	v_max_f32_e32 v214, v214, v214
	v_max_f32_e32 v215, v215, v215
	v_max_f32_e32 v216, v216, v216
	v_max_f32_e32 v217, v217, v217
	v_max_f32_e32 v218, v218, v218
	v_max_f32_e32 v219, v219, v219
	v_max_f32_e32 v220, v220, v220
	v_max_f32_e32 v221, v221, v221
	v_max_f32_e32 v214, 0xda24260, v214
	v_max_f32_e32 v215, 0xda24260, v215
	v_max_f32_e32 v216, 0xda24260, v216
	v_max_f32_e32 v217, 0xda24260, v217
	v_max_f32_e32 v218, 0xda24260, v218
	v_max_f32_e32 v219, 0xda24260, v219
	v_max_f32_e32 v220, 0xda24260, v220
	v_max_f32_e32 v221, 0xda24260, v221
	v_pk_mul_f32 v[222:223], v[100:101], v[214:215]
	v_pk_mul_f32 v[224:225], v[102:103], v[216:217]
	v_pk_mul_f32 v[226:227], v[96:97], v[218:219]
	v_pk_mul_f32 v[228:229], v[98:99], v[220:221]
	v_cvt_pk_bf16_f32 v230, v222, v223
	v_cvt_pk_bf16_f32 v231, v224, v225
	v_cvt_pk_bf16_f32 v232, v226, v227
	v_cvt_pk_bf16_f32 v233, v228, v229
	global_store_dwordx4 v234, v[230:233], s[100:101]
	v_lshlrev_b32_e32 v214, 16, v174
	v_and_b32_e32 v215, 0xffff0000, v174
	v_lshlrev_b32_e32 v216, 16, v175
	v_and_b32_e32 v217, 0xffff0000, v175
	v_lshlrev_b32_e32 v218, 16, v176
	v_and_b32_e32 v219, 0xffff0000, v176
	v_lshlrev_b32_e32 v220, 16, v177
	v_and_b32_e32 v221, 0xffff0000, v177
	v_max_f32_e32 v214, v214, v214
	v_max_f32_e32 v215, v215, v215
	v_max_f32_e32 v216, v216, v216
	v_max_f32_e32 v217, v217, v217
	v_max_f32_e32 v218, v218, v218
	v_max_f32_e32 v219, v219, v219
	v_max_f32_e32 v220, v220, v220
	v_max_f32_e32 v221, v221, v221
	v_max_f32_e32 v214, 0xda24260, v214
	v_max_f32_e32 v215, 0xda24260, v215
	v_max_f32_e32 v216, 0xda24260, v216
	v_max_f32_e32 v217, 0xda24260, v217
	v_max_f32_e32 v218, 0xda24260, v218
	v_max_f32_e32 v219, 0xda24260, v219
	v_max_f32_e32 v220, 0xda24260, v220
	v_max_f32_e32 v221, 0xda24260, v221
	v_pk_mul_f32 v[222:223], v[68:69], v[214:215]
	v_pk_mul_f32 v[224:225], v[70:71], v[216:217]
	v_pk_mul_f32 v[226:227], v[64:65], v[218:219]
	v_pk_mul_f32 v[228:229], v[66:67], v[220:221]
	v_cvt_pk_bf16_f32 v230, v222, v223
	v_cvt_pk_bf16_f32 v231, v224, v225
	v_cvt_pk_bf16_f32 v232, v226, v227
	v_cvt_pk_bf16_f32 v233, v228, v229
	global_store_dwordx4 v234, v[230:233], s[100:101] offset:256
	s_add_u32 s100, s100, 0x28000
	s_addc_u32 s101, s101, 0
	v_lshlrev_b32_e32 v214, 16, v178
	v_and_b32_e32 v215, 0xffff0000, v178
	v_lshlrev_b32_e32 v216, 16, v179
	v_and_b32_e32 v217, 0xffff0000, v179
	v_lshlrev_b32_e32 v218, 16, v180
	v_and_b32_e32 v219, 0xffff0000, v180
	v_lshlrev_b32_e32 v220, 16, v181
	v_and_b32_e32 v221, 0xffff0000, v181
	v_max_f32_e32 v214, v214, v214
	v_max_f32_e32 v215, v215, v215
	v_max_f32_e32 v216, v216, v216
	v_max_f32_e32 v217, v217, v217
	v_max_f32_e32 v218, v218, v218
	v_max_f32_e32 v219, v219, v219
	v_max_f32_e32 v220, v220, v220
	v_max_f32_e32 v221, v221, v221
	v_max_f32_e32 v214, 0xda24260, v214
	v_max_f32_e32 v215, 0xda24260, v215
	v_max_f32_e32 v216, 0xda24260, v216
	v_max_f32_e32 v217, 0xda24260, v217
	v_max_f32_e32 v218, 0xda24260, v218
	v_max_f32_e32 v219, 0xda24260, v219
	v_max_f32_e32 v220, 0xda24260, v220
	v_max_f32_e32 v221, 0xda24260, v221
	v_pk_mul_f32 v[222:223], v[60:61], v[214:215]
	v_pk_mul_f32 v[224:225], v[62:63], v[216:217]
	v_pk_mul_f32 v[226:227], v[56:57], v[218:219]
	v_pk_mul_f32 v[228:229], v[58:59], v[220:221]
	v_cvt_pk_bf16_f32 v230, v222, v223
	v_cvt_pk_bf16_f32 v231, v224, v225
	v_cvt_pk_bf16_f32 v232, v226, v227
	v_cvt_pk_bf16_f32 v233, v228, v229
	global_store_dwordx4 v234, v[230:233], s[100:101]
	v_lshlrev_b32_e32 v214, 16, v186
	v_and_b32_e32 v215, 0xffff0000, v186
	v_lshlrev_b32_e32 v216, 16, v187
	v_and_b32_e32 v217, 0xffff0000, v187
	v_lshlrev_b32_e32 v218, 16, v188
	v_and_b32_e32 v219, 0xffff0000, v188
	v_lshlrev_b32_e32 v220, 16, v189
	v_and_b32_e32 v221, 0xffff0000, v189
	v_max_f32_e32 v214, v214, v214
	v_max_f32_e32 v215, v215, v215
	v_max_f32_e32 v216, v216, v216
	v_max_f32_e32 v217, v217, v217
	v_max_f32_e32 v218, v218, v218
	v_max_f32_e32 v219, v219, v219
	v_max_f32_e32 v220, v220, v220
	v_max_f32_e32 v221, v221, v221
	v_max_f32_e32 v214, 0xda24260, v214
	v_max_f32_e32 v215, 0xda24260, v215
	v_max_f32_e32 v216, 0xda24260, v216
	v_max_f32_e32 v217, 0xda24260, v217
	v_max_f32_e32 v218, 0xda24260, v218
	v_max_f32_e32 v219, 0xda24260, v219
	v_max_f32_e32 v220, 0xda24260, v220
	v_max_f32_e32 v221, 0xda24260, v221
	v_pk_mul_f32 v[222:223], v[28:29], v[214:215]
	v_pk_mul_f32 v[224:225], v[30:31], v[216:217]
	v_pk_mul_f32 v[226:227], v[24:25], v[218:219]
	v_pk_mul_f32 v[228:229], v[26:27], v[220:221]
	v_cvt_pk_bf16_f32 v230, v222, v223
	v_cvt_pk_bf16_f32 v231, v224, v225
	v_cvt_pk_bf16_f32 v232, v226, v227
	v_cvt_pk_bf16_f32 v233, v228, v229
	global_store_dwordx4 v234, v[230:233], s[100:101] offset:256
	s_add_u32 s100, s100, 0x8000
	s_addc_u32 s101, s101, 0
	v_lshlrev_b32_e32 v214, 16, v190
	v_and_b32_e32 v215, 0xffff0000, v190
	v_lshlrev_b32_e32 v216, 16, v191
	v_and_b32_e32 v217, 0xffff0000, v191
	v_lshlrev_b32_e32 v218, 16, v192
	v_and_b32_e32 v219, 0xffff0000, v192
	v_lshlrev_b32_e32 v220, 16, v193
	v_and_b32_e32 v221, 0xffff0000, v193
	v_max_f32_e32 v214, v214, v214
	v_max_f32_e32 v215, v215, v215
	v_max_f32_e32 v216, v216, v216
	v_max_f32_e32 v217, v217, v217
	v_max_f32_e32 v218, v218, v218
	v_max_f32_e32 v219, v219, v219
	v_max_f32_e32 v220, v220, v220
	v_max_f32_e32 v221, v221, v221
	v_max_f32_e32 v214, 0xda24260, v214
; __device__ __forceinline__ u32x4 pack8(f32x4 a, f32x4 b) { u32x4 w; w.x = cvt_pk(a[0], a[1]); w.y = cvt_pk(a[2], a[3]); w.z = cvt_pk(b[0], b[1]); w.w = cvt_pk(b[2], b[3]); return w; }
;     __device__ __forceinline__ void operator()(f32x4 (&acc)[2][2][4][2], const pg8::Unit& u, int wr, int wc, int fr, int fq) const {
;     ...
; #pragma unroll
;             for (int m = 0; m < 4; ++m) { const size_t ro = (size_t)(row0 + ai * 128 + m * 16) * DM + colt;
; #pragma unroll
;                 for (int bj = 0; bj < 2; ++bj) { const size_t o = ro + bj * 128;
;     ...
;                     } else { f32x4 v0 = acc[ai][bj][m][0], v1 = acc[ai][bj][m][1];
; #pragma unroll
;                         for (int e = 0; e < 4; ++e) { v0[e] *= a8[e]; v1[e] *= a8[4 + e]; }
;                         *(u32x4*)(MG + o) = pack8(v0, v1); } } }
	v_max_f32_e32 v215, 0xda24260, v215
	v_max_f32_e32 v216, 0xda24260, v216
	v_max_f32_e32 v217, 0xda24260, v217
	v_max_f32_e32 v218, 0xda24260, v218
	v_max_f32_e32 v219, 0xda24260, v219
	v_max_f32_e32 v220, 0xda24260, v220
	v_max_f32_e32 v221, 0xda24260, v221
	v_pk_mul_f32 v[222:223], v[52:53], v[214:215]
	v_pk_mul_f32 v[224:225], v[54:55], v[216:217]
	v_pk_mul_f32 v[226:227], v[48:49], v[218:219]
	v_pk_mul_f32 v[228:229], v[50:51], v[220:221]
	v_cvt_pk_bf16_f32 v230, v222, v223
	v_cvt_pk_bf16_f32 v231, v224, v225
	v_cvt_pk_bf16_f32 v232, v226, v227
	v_cvt_pk_bf16_f32 v233, v228, v229
	global_store_dwordx4 v234, v[230:233], s[100:101]
	v_lshlrev_b32_e32 v214, 16, v194
	v_and_b32_e32 v215, 0xffff0000, v194
	v_lshlrev_b32_e32 v216, 16, v195
	v_and_b32_e32 v217, 0xffff0000, v195
	v_lshlrev_b32_e32 v218, 16, v196
	v_and_b32_e32 v219, 0xffff0000, v196
	v_lshlrev_b32_e32 v220, 16, v197
	v_and_b32_e32 v221, 0xffff0000, v197
	v_max_f32_e32 v214, v214, v214
	v_max_f32_e32 v215, v215, v215
	v_max_f32_e32 v216, v216, v216
	v_max_f32_e32 v217, v217, v217
	v_max_f32_e32 v218, v218, v218
	v_max_f32_e32 v219, v219, v219
	v_max_f32_e32 v220, v220, v220
	v_max_f32_e32 v221, v221, v221
	v_max_f32_e32 v214, 0xda24260, v214
	v_max_f32_e32 v215, 0xda24260, v215
	v_max_f32_e32 v216, 0xda24260, v216
	v_max_f32_e32 v217, 0xda24260, v217
	v_max_f32_e32 v218, 0xda24260, v218
	v_max_f32_e32 v219, 0xda24260, v219
	v_max_f32_e32 v220, 0xda24260, v220
	v_max_f32_e32 v221, 0xda24260, v221
	v_pk_mul_f32 v[222:223], v[20:21], v[214:215]
	v_pk_mul_f32 v[224:225], v[22:23], v[216:217]
	v_pk_mul_f32 v[226:227], v[16:17], v[218:219]
	v_pk_mul_f32 v[228:229], v[18:19], v[220:221]
	v_cvt_pk_bf16_f32 v230, v222, v223
	v_cvt_pk_bf16_f32 v231, v224, v225
	v_cvt_pk_bf16_f32 v232, v226, v227
	v_cvt_pk_bf16_f32 v233, v228, v229
	global_store_dwordx4 v234, v[230:233], s[100:101] offset:256
	s_add_u32 s100, s100, 0x8000
	s_addc_u32 s101, s101, 0
	v_lshlrev_b32_e32 v214, 16, v198
	v_and_b32_e32 v215, 0xffff0000, v198
	v_lshlrev_b32_e32 v216, 16, v199
	v_and_b32_e32 v217, 0xffff0000, v199
	v_lshlrev_b32_e32 v218, 16, v200
	v_and_b32_e32 v219, 0xffff0000, v200
	v_lshlrev_b32_e32 v220, 16, v201
	v_and_b32_e32 v221, 0xffff0000, v201
	v_max_f32_e32 v214, v214, v214
	v_max_f32_e32 v215, v215, v215
	v_max_f32_e32 v216, v216, v216
	v_max_f32_e32 v217, v217, v217
	v_max_f32_e32 v218, v218, v218
	v_max_f32_e32 v219, v219, v219
	v_max_f32_e32 v220, v220, v220
	v_max_f32_e32 v221, v221, v221
	v_max_f32_e32 v214, 0xda24260, v214
	v_max_f32_e32 v215, 0xda24260, v215
	v_max_f32_e32 v216, 0xda24260, v216
	v_max_f32_e32 v217, 0xda24260, v217
	v_max_f32_e32 v218, 0xda24260, v218
	v_max_f32_e32 v219, 0xda24260, v219
	v_max_f32_e32 v220, 0xda24260, v220
	v_max_f32_e32 v221, 0xda24260, v221
	v_pk_mul_f32 v[222:223], v[44:45], v[214:215]
	v_pk_mul_f32 v[224:225], v[46:47], v[216:217]
	v_pk_mul_f32 v[226:227], v[40:41], v[218:219]
	v_pk_mul_f32 v[228:229], v[42:43], v[220:221]
	v_cvt_pk_bf16_f32 v230, v222, v223
	v_cvt_pk_bf16_f32 v231, v224, v225
	v_cvt_pk_bf16_f32 v232, v226, v227
	v_cvt_pk_bf16_f32 v233, v228, v229
	global_store_dwordx4 v234, v[230:233], s[100:101]
	v_lshlrev_b32_e32 v214, 16, v202
	v_and_b32_e32 v215, 0xffff0000, v202
	v_lshlrev_b32_e32 v216, 16, v203
	v_and_b32_e32 v217, 0xffff0000, v203
	v_lshlrev_b32_e32 v218, 16, v204
	v_and_b32_e32 v219, 0xffff0000, v204
	v_lshlrev_b32_e32 v220, 16, v205
	v_and_b32_e32 v221, 0xffff0000, v205
	v_max_f32_e32 v214, v214, v214
	v_max_f32_e32 v215, v215, v215
	v_max_f32_e32 v216, v216, v216
	v_max_f32_e32 v217, v217, v217
	v_max_f32_e32 v218, v218, v218
	v_max_f32_e32 v219, v219, v219
	v_max_f32_e32 v220, v220, v220
	v_max_f32_e32 v221, v221, v221
	v_max_f32_e32 v214, 0xda24260, v214
	v_max_f32_e32 v215, 0xda24260, v215
	v_max_f32_e32 v216, 0xda24260, v216
	v_max_f32_e32 v217, 0xda24260, v217
	v_max_f32_e32 v218, 0xda24260, v218
	v_max_f32_e32 v219, 0xda24260, v219
	v_max_f32_e32 v220, 0xda24260, v220
	v_max_f32_e32 v221, 0xda24260, v221
	v_pk_mul_f32 v[222:223], v[12:13], v[214:215]
	v_pk_mul_f32 v[224:225], v[14:15], v[216:217]
	v_pk_mul_f32 v[226:227], v[8:9], v[218:219]
	v_pk_mul_f32 v[228:229], v[10:11], v[220:221]
	v_cvt_pk_bf16_f32 v230, v222, v223
	v_cvt_pk_bf16_f32 v231, v224, v225
	v_cvt_pk_bf16_f32 v232, v226, v227
	v_cvt_pk_bf16_f32 v233, v228, v229
	global_store_dwordx4 v234, v[230:233], s[100:101] offset:256
	s_add_u32 s100, s100, 0x8000
	s_addc_u32 s101, s101, 0
	v_lshlrev_b32_e32 v214, 16, v206
	v_and_b32_e32 v215, 0xffff0000, v206
	v_lshlrev_b32_e32 v216, 16, v207
	v_and_b32_e32 v217, 0xffff0000, v207
	v_lshlrev_b32_e32 v218, 16, v208
	v_and_b32_e32 v219, 0xffff0000, v208
	v_lshlrev_b32_e32 v220, 16, v209
	v_and_b32_e32 v221, 0xffff0000, v209
	v_max_f32_e32 v214, v214, v214
	v_max_f32_e32 v215, v215, v215
	v_max_f32_e32 v216, v216, v216
	v_max_f32_e32 v217, v217, v217
	v_max_f32_e32 v218, v218, v218
	v_max_f32_e32 v219, v219, v219
	v_max_f32_e32 v220, v220, v220
	v_max_f32_e32 v221, v221, v221
	v_max_f32_e32 v214, 0xda24260, v214
	v_max_f32_e32 v215, 0xda24260, v215
	v_max_f32_e32 v216, 0xda24260, v216
	v_max_f32_e32 v217, 0xda24260, v217
	v_max_f32_e32 v218, 0xda24260, v218
	v_max_f32_e32 v219, 0xda24260, v219
	v_max_f32_e32 v220, 0xda24260, v220
	v_max_f32_e32 v221, 0xda24260, v221
	v_pk_mul_f32 v[222:223], v[36:37], v[214:215]
	v_pk_mul_f32 v[224:225], v[38:39], v[216:217]
	v_pk_mul_f32 v[226:227], v[32:33], v[218:219]
	v_pk_mul_f32 v[228:229], v[34:35], v[220:221]
	v_cvt_pk_bf16_f32 v230, v222, v223
	v_cvt_pk_bf16_f32 v231, v224, v225
	v_cvt_pk_bf16_f32 v232, v226, v227
	v_cvt_pk_bf16_f32 v233, v228, v229
	global_store_dwordx4 v234, v[230:233], s[100:101]
	v_lshlrev_b32_e32 v214, 16, v210
	v_and_b32_e32 v215, 0xffff0000, v210
	v_lshlrev_b32_e32 v216, 16, v211
	v_and_b32_e32 v217, 0xffff0000, v211
	v_lshlrev_b32_e32 v218, 16, v212
	v_and_b32_e32 v219, 0xffff0000, v212
	v_lshlrev_b32_e32 v220, 16, v213
	v_and_b32_e32 v221, 0xffff0000, v213
	v_max_f32_e32 v214, v214, v214
	v_max_f32_e32 v215, v215, v215
	v_max_f32_e32 v216, v216, v216
	v_max_f32_e32 v217, v217, v217
	v_max_f32_e32 v218, v218, v218
	v_max_f32_e32 v219, v219, v219
	v_max_f32_e32 v220, v220, v220
	v_max_f32_e32 v221, v221, v221
	v_max_f32_e32 v214, 0xda24260, v214
	v_max_f32_e32 v215, 0xda24260, v215
	v_max_f32_e32 v216, 0xda24260, v216
	v_max_f32_e32 v217, 0xda24260, v217
	v_max_f32_e32 v218, 0xda24260, v218
	v_max_f32_e32 v219, 0xda24260, v219
	v_max_f32_e32 v220, 0xda24260, v220
	v_max_f32_e32 v221, 0xda24260, v221
	v_pk_mul_f32 v[222:223], v[4:5], v[214:215]
	v_pk_mul_f32 v[224:225], v[6:7], v[216:217]
	v_pk_mul_f32 v[226:227], v[0:1], v[218:219]
	v_pk_mul_f32 v[228:229], v[2:3], v[220:221]
	v_cvt_pk_bf16_f32 v230, v222, v223
	v_cvt_pk_bf16_f32 v231, v224, v225
	v_cvt_pk_bf16_f32 v232, v226, v227
	v_cvt_pk_bf16_f32 v233, v228, v229
	global_store_dwordx4 v234, v[230:233], s[100:101] offset:256
	s_add_u32 s100, s100, 0x28000
	s_addc_u32 s101, s101, 0
	s_mov_b64 s[4:5], 0
.Lbr_done:
.LBB0_701:
	s_andn2_b64 vcc, exec, s[26:27]
	s_mov_b64 s[26:27], -1
	s_cbranch_vccnz .LBB0_640
	s_and_b64 vcc, exec, s[4:5]
	s_cbranch_vccnz .LBB0_704
	v_mov_b32_e32 v0, 0
	v_mov_b32_e32 v1, v0
	v_mov_b32_e32 v2, v0
	v_mov_b32_e32 v3, v0
	v_mov_b32_e32 v4, v0
	v_mov_b32_e32 v5, v0
	v_mov_b32_e32 v6, v0
	v_mov_b32_e32 v7, v0
	v_mov_b32_e32 v8, v0
	v_mov_b32_e32 v9, v0
	v_mov_b32_e32 v10, v0
	v_mov_b32_e32 v11, v0
	v_mov_b32_e32 v12, v0
	v_mov_b32_e32 v13, v0
	v_mov_b32_e32 v14, v0
	v_mov_b32_e32 v15, v0
	v_mov_b32_e32 v16, v0
	v_mov_b32_e32 v17, v0
	v_mov_b32_e32 v18, v0
	v_mov_b32_e32 v19, v0
	v_mov_b32_e32 v20, v0
	v_mov_b32_e32 v21, v0
	v_mov_b32_e32 v22, v0
	v_mov_b32_e32 v23, v0
	v_mov_b32_e32 v24, v0
	v_mov_b32_e32 v25, v0
	v_mov_b32_e32 v26, v0
	v_mov_b32_e32 v27, v0
	v_mov_b32_e32 v28, v0
	v_mov_b32_e32 v29, v0
	v_mov_b32_e32 v30, v0
	v_mov_b32_e32 v31, v0
	v_mov_b32_e32 v32, v0
	v_mov_b32_e32 v33, v0
	v_mov_b32_e32 v34, v0
	v_mov_b32_e32 v35, v0
	v_mov_b32_e32 v36, v0
	v_mov_b32_e32 v37, v0
	v_mov_b32_e32 v38, v0
	v_mov_b32_e32 v39, v0
	v_mov_b32_e32 v40, v0
	v_mov_b32_e32 v41, v0
	v_mov_b32_e32 v42, v0
	v_mov_b32_e32 v43, v0
	v_mov_b32_e32 v44, v0
	v_mov_b32_e32 v45, v0
	v_mov_b32_e32 v46, v0
	v_mov_b32_e32 v47, v0
	v_mov_b32_e32 v48, v0
	v_mov_b32_e32 v49, v0
	v_mov_b32_e32 v50, v0
	v_mov_b32_e32 v51, v0
	v_mov_b32_e32 v52, v0
	v_mov_b32_e32 v53, v0
	v_mov_b32_e32 v54, v0
	v_mov_b32_e32 v55, v0
	v_mov_b32_e32 v56, v0
	v_mov_b32_e32 v57, v0
	v_mov_b32_e32 v58, v0
	v_mov_b32_e32 v59, v0
	v_mov_b32_e32 v60, v0
	v_mov_b32_e32 v61, v0
	v_mov_b32_e32 v62, v0
	v_mov_b32_e32 v63, v0
	v_mov_b32_e32 v64, v0
	v_mov_b32_e32 v65, v0
	v_mov_b32_e32 v66, v0
	v_mov_b32_e32 v67, v0
	v_mov_b32_e32 v68, v0
	v_mov_b32_e32 v69, v0
	v_mov_b32_e32 v70, v0
	v_mov_b32_e32 v71, v0
	v_mov_b32_e32 v72, v0
	v_mov_b32_e32 v73, v0
	v_mov_b32_e32 v74, v0
	v_mov_b32_e32 v75, v0
	v_mov_b32_e32 v76, v0
	v_mov_b32_e32 v77, v0
	v_mov_b32_e32 v78, v0
	v_mov_b32_e32 v79, v0
	v_mov_b32_e32 v80, v0
	v_mov_b32_e32 v81, v0
	v_mov_b32_e32 v82, v0
	v_mov_b32_e32 v83, v0
	v_mov_b32_e32 v84, v0
	v_mov_b32_e32 v85, v0
	v_mov_b32_e32 v86, v0
	v_mov_b32_e32 v87, v0
	v_mov_b32_e32 v88, v0
	v_mov_b32_e32 v89, v0
	v_mov_b32_e32 v90, v0
	v_mov_b32_e32 v91, v0
	v_mov_b32_e32 v92, v0
	v_mov_b32_e32 v93, v0
	v_mov_b32_e32 v94, v0
	v_mov_b32_e32 v95, v0
	v_mov_b32_e32 v96, v0
	v_mov_b32_e32 v97, v0
	v_mov_b32_e32 v98, v0
	v_mov_b32_e32 v99, v0
	v_mov_b32_e32 v100, v0
	v_mov_b32_e32 v101, v0
	v_mov_b32_e32 v102, v0
	v_mov_b32_e32 v103, v0
	v_mov_b32_e32 v104, v0
	v_mov_b32_e32 v105, v0
	v_mov_b32_e32 v106, v0
	v_mov_b32_e32 v107, v0
	v_mov_b32_e32 v108, v0
	v_mov_b32_e32 v109, v0
	v_mov_b32_e32 v110, v0
	v_mov_b32_e32 v111, v0
	v_mov_b32_e32 v112, v0
	v_mov_b32_e32 v113, v0
	v_mov_b32_e32 v114, v0
	v_mov_b32_e32 v115, v0
	v_mov_b32_e32 v116, v0
	v_mov_b32_e32 v117, v0
	v_mov_b32_e32 v118, v0
	v_mov_b32_e32 v119, v0
	v_mov_b32_e32 v120, v0
	v_mov_b32_e32 v121, v0
	v_mov_b32_e32 v122, v0
	v_mov_b32_e32 v123, v0
	v_mov_b32_e32 v124, v0
	v_mov_b32_e32 v125, v0
	v_mov_b32_e32 v126, v0
	v_mov_b32_e32 v127, v0
.LBB0_704:
	s_andn2_b64 vcc, exec, s[6:7]
	s_cbranch_vccnz .LBB0_639
	s_barrier
	s_branch .LBB0_639
.LBB0_721:
	s_waitcnt vmcnt(0)
	s_barrier
